# P1 row loop: wave sums via DPP row ops and permlane swaps instead of ds_bpermute butterflies (bit-identical sums)
# baseline (speedup 1.0000x reference)
; #define GAS __attribute__((address_space(1)))
; __device__ __forceinline__ unsigned pk2(float lo, float hi) { return pg8::cvt_pk_bf16(lo, hi); }
; __device__ __forceinline__ float wave_sum(float v) {
; #pragma unroll
;     for (int o = 1; o < 64; o <<= 1) v += __shfl_xor(v, o);
;     return v;
; }
; template <int LO, int HI> __global__ void __launch_bounds__(NWAVES * 64, 2) fox_fwd(Args args) {
;     ...
;         for (int r = 0; r < 16; ++r) { const int m = m0 + r;
;             const GAS float* xr = (const GAS float*)(x + (size_t)m * D);
;             f32x4 v[4]; float s2 = 0.f;
; #pragma unroll
;             for (int j = 0; j < 4; ++j) { v[j] = *(const GAS f32x4*)(xr + P1COL(j)); s2 += (v[j][0] * v[j][0] + v[j][1] * v[j][1]) + (v[j][2] * v[j][2] + v[j][3] * v[j][3]); }
;             const float rstd = 1.0f / sqrtf(wave_sum(s2) * (1.0f / D) + EPS);
; #pragma unroll
;             for (int j = 0; j < 4; ++j) v[j] = v[j] * rstd * gm[j] + sh[j];
; #pragma unroll
;             for (int j = 0; j < 2; ++j) { v4u o; o.x = pk2(v[2 * j][0], v[2 * j][1]); o.y = pk2(v[2 * j][2], v[2 * j][3]); o.z = pk2(v[2 * j + 1][0], v[2 * j + 1][1]); o.w = pk2(v[2 * j + 1][2], v[2 * j + 1][3]);
;                 *(GAS v4u*)(HB + (size_t)m * D + 8 * lane + 512 * j) = o; }
.LBB0_131:
	v_lshl_add_u64 v[60:61], v[54:55], 0, s[30:31]
	v_add_co_u32_e32 v88, vcc, s48, v60
	v_lshl_add_u64 v[86:87], v[60:61], 0, s[34:35]
	s_nop 0
	v_addc_co_u32_e32 v89, vcc, 0, v61, vcc
	v_lshl_add_u64 v[90:91], v[60:61], 0, s[38:39]
	global_load_dwordx4 v[60:63], v[88:89], off
	global_load_dwordx4 v[74:77], v[86:87], off offset:16
	global_load_dwordx4 v[78:81], v[90:91], off offset:16
	global_load_dwordx4 v[82:85], v[88:89], off offset:2048
	s_cmp_eq_u32 s30, 0
	s_waitcnt vmcnt(3)
	v_pk_mul_f32 v[86:87], v[62:63], v[62:63]
	v_pk_mul_f32 v[88:89], v[60:61], v[60:61]
	s_waitcnt vmcnt(2)
	v_pk_mul_f32 v[90:91], v[76:77], v[76:77]
	v_pk_mul_f32 v[92:93], v[74:75], v[74:75]
	v_pk_mov_b32 v[96:97], v[88:89], v[86:87] op_sel:[1,0]
	v_mov_b32_e32 v89, v87
	v_pk_mov_b32 v[86:87], v[92:93], v[90:91] op_sel:[1,0]
	v_mov_b32_e32 v93, v91
	s_waitcnt vmcnt(0)
	v_mul_f32_e32 v36, v83, v83
	v_mul_f32_e32 v94, v85, v85
	v_pk_add_f32 v[88:89], v[96:97], v[88:89]
	v_pk_add_f32 v[86:87], v[86:87], v[92:93]
	v_mul_f32_e32 v59, v78, v78
	v_mul_f32_e32 v67, v79, v79
	v_mul_f32_e32 v98, v80, v80
	v_mul_f32_e32 v99, v81, v81
	v_pk_fma_f32 v[90:91], v[82:83], v[82:83], v[36:37] op_sel_hi:[1,1,0]
	v_pk_fma_f32 v[94:95], v[84:85], v[84:85], v[94:95] op_sel_hi:[1,1,0]
	v_pk_add_f32 v[88:89], v[88:89], v[88:89] op_sel:[0,1] op_sel_hi:[1,0]
	v_pk_add_f32 v[86:87], v[86:87], v[86:87] op_sel:[0,1] op_sel_hi:[1,0]
	v_mov_b32_e32 v91, v98
	v_mov_b32_e32 v95, v99
	v_mov_b32_e32 v89, v59
	v_mov_b32_e32 v87, v67
	v_pk_add_f32 v[90:91], v[90:91], v[94:95]
	v_pk_add_f32 v[86:87], v[88:89], v[86:87]
	s_nop 0
	v_pk_add_f32 v[86:87], v[86:87], v[90:91]
	s_nop 0
	v_add_f32_e32 v36, v86, v87
	s_waitcnt lgkmcnt(0)
	s_nop 1
	v_add_f32_dpp v59, v36, v36 quad_perm:[1,0,3,2] row_mask:0xf bank_mask:0xf
	s_nop 1
	v_add_f32_dpp v36, v59, v59 quad_perm:[2,3,0,1] row_mask:0xf bank_mask:0xf
	s_nop 1
	v_add_f32_dpp v59, v36, v36 row_half_mirror row_mask:0xf bank_mask:0xf
	s_nop 1
	v_add_f32_dpp v36, v59, v59 row_mirror row_mask:0xf bank_mask:0xf
	v_mov_b32_e32 v59, v36
	s_nop 1
	v_permlane16_swap_b32_e32 v59, v36
	v_add_f32_e32 v59, v59, v36
	v_mov_b32_e32 v36, v59
	s_nop 1
	v_permlane32_swap_b32_e32 v36, v59
	v_add_f32_e32 v36, v36, v59
	v_fmamk_f32 v36, v36, 0x3a800000, v69
	v_mul_f32_e32 v59, 0x4f800000, v36
	v_cmp_gt_f32_e32 vcc, s45, v36
	s_nop 1
	v_cndmask_b32_e32 v36, v36, v59, vcc
	v_sqrt_f32_e32 v59, v36
	s_nop 0
	v_add_u32_e32 v67, -1, v59
	v_add_u32_e32 v86, 1, v59
	v_fma_f32 v87, -v67, v59, v36
	v_fma_f32 v88, -v86, v59, v36
	v_cmp_ge_f32_e64 s[20:21], 0, v87
	s_nop 1
	v_cndmask_b32_e64 v59, v59, v67, s[20:21]
	v_cmp_lt_f32_e64 s[20:21], 0, v88
	s_nop 1
	v_cndmask_b32_e64 v59, v59, v86, s[20:21]
	v_mul_f32_e32 v67, 0x37800000, v59
	v_cndmask_b32_e32 v59, v59, v67, vcc
	v_cmp_class_f32_e32 vcc, v36, v70
	s_nop 1
	v_cndmask_b32_e32 v36, v59, v36, vcc
	v_div_scale_f32 v59, s[20:21], v36, v36, 1.0
	v_rcp_f32_e32 v86, v59
	v_div_scale_f32 v67, vcc, 1.0, v36, 1.0
	v_fma_f32 v87, -v59, v86, 1.0
	v_fmac_f32_e32 v86, v87, v86
	v_mul_f32_e32 v87, v67, v86
	v_fma_f32 v88, -v59, v87, v67
	v_fmac_f32_e32 v87, v88, v86
	v_fma_f32 v59, -v59, v87, v67
	v_div_fmas_f32 v59, v59, v86, v87
	v_div_fixup_f32 v36, v59, v36, 1.0
	v_pk_mul_f32 v[60:61], v[36:37], v[60:61] op_sel_hi:[0,1]
	v_pk_mul_f32 v[62:63], v[36:37], v[62:63] op_sel_hi:[0,1]
	v_pk_mul_f32 v[74:75], v[36:37], v[74:75] op_sel_hi:[0,1]
	v_pk_mul_f32 v[76:77], v[36:37], v[76:77] op_sel_hi:[0,1]
	v_pk_mul_f32 v[82:83], v[36:37], v[82:83] op_sel_hi:[0,1]
	v_pk_mul_f32 v[84:85], v[36:37], v[84:85] op_sel_hi:[0,1]
	v_pk_mul_f32 v[78:79], v[36:37], v[78:79] op_sel_hi:[0,1]
	v_pk_mul_f32 v[80:81], v[36:37], v[80:81] op_sel_hi:[0,1]
	v_pk_fma_f32 v[162:163], v[38:39], v[62:63], v[8:9]
	v_pk_fma_f32 v[214:215], v[40:41], v[60:61], v[6:7]
	v_pk_fma_f32 v[216:217], v[42:43], v[76:77], v[4:5]
	v_pk_fma_f32 v[218:219], v[44:45], v[74:75], v[2:3]
	v_cvt_pk_bf16_f32 v74, v214, v215
	v_cvt_pk_bf16_f32 v75, v162, v163
	v_pk_fma_f32 v[60:61], v[46:47], v[84:85], v[16:17]
	v_cvt_pk_bf16_f32 v76, v218, v219
	v_cvt_pk_bf16_f32 v77, v216, v217
	v_pk_fma_f32 v[62:63], v[48:49], v[82:83], v[14:15]
	v_pk_fma_f32 v[220:221], v[50:51], v[80:81], v[12:13]
	v_pk_fma_f32 v[222:223], v[52:53], v[78:79], v[10:11]
	global_store_dwordx4 v[56:57], v[74:77], off offset:-1024
	s_nop 1
	v_cvt_pk_bf16_f32 v74, v62, v63
	v_cvt_pk_bf16_f32 v75, v60, v61
	v_cvt_pk_bf16_f32 v76, v222, v223
	v_cvt_pk_bf16_f32 v77, v220, v221
	ds_read_b128 v[78:81], v72
	ds_read_b128 v[82:85], v72 offset:16
	ds_read_b128 v[86:89], v72 offset:2048
	ds_read_b128 v[90:93], v72 offset:2064
	ds_read_b128 v[94:97], v72 offset:4096
	ds_read_b128 v[98:101], v72 offset:4112
	ds_read_b128 v[102:105], v72 offset:6144
	ds_read_b128 v[106:109], v72 offset:6160
	ds_read_b128 v[110:113], v72 offset:8192
	ds_read_b128 v[114:117], v72 offset:8208
	ds_read_b128 v[118:121], v72 offset:10240
	ds_read_b128 v[122:125], v72 offset:10256
	ds_read_b128 v[126:129], v72 offset:12288
	ds_read_b128 v[130:133], v72 offset:12304
	ds_read_b128 v[134:137], v72 offset:14336
	ds_read_b128 v[138:141], v72 offset:14352
	ds_read_b128 v[142:145], v72 offset:16384
	ds_read_b128 v[146:149], v72 offset:16400
	ds_read_b128 v[150:153], v72 offset:18432
	ds_read_b128 v[154:157], v72 offset:18448
	ds_read_b128 v[158:161], v72 offset:20480
	ds_read_b128 v[170:173], v72 offset:20496
	ds_read_b128 v[174:177], v72 offset:22528
	ds_read_b128 v[178:181], v72 offset:22544
	ds_read_b128 v[182:185], v72 offset:24576
	ds_read_b128 v[186:189], v72 offset:24592
	ds_read_b128 v[190:193], v72 offset:26624
	ds_read_b128 v[194:197], v72 offset:26640
	ds_read_b128 v[198:201], v72 offset:28672
	ds_read_b128 v[202:205], v72 offset:28688
	ds_read_b128 v[206:209], v72 offset:30720
	ds_read_b128 v[210:213], v72 offset:30736
	s_waitcnt lgkmcnt(14)
; #define LAS __attribute__((address_space(3)))
; __device__ __forceinline__ float wave_sum(float v) {
; #pragma unroll
;     for (int o = 1; o < 64; o <<= 1) v += __shfl_xor(v, o);
;     return v;
; }
; template <int LO, int HI> __global__ void __launch_bounds__(NWAVES * 64, 2) fox_fwd(Args args) {
;     ...
;             float fl[8];
; #pragma unroll
;             for (int q = 0; q < 8; ++q) { float a = 0.f;
; #pragma unroll
;                 for (int j = 0; j < 4; ++j) { const f32x4 w = *(const LAS f32x4*)(wf + q * 1024 + P1COL(j)); a += (v[j][0] * w[0] + v[j][1] * w[1]) + (v[j][2] * w[2] + v[j][3] * w[3]); }
;                 fl[q] = wave_sum(a); }
	v_mul_f32_e32 v59, v215, v79
	v_mul_f32_e32 v67, v163, v81
	v_mul_f32_e32 v89, v61, v89
	v_mul_f32_e32 v91, v223, v91
	v_mul_f32_e32 v95, v215, v95
	v_mul_f32_e32 v97, v163, v97
	global_store_dwordx4 v[56:57], v[74:77], off
	v_mul_f32_e32 v224, v219, v83
	v_mul_f32_e32 v225, v217, v85
	v_mul_f32_e32 v87, v63, v87
	v_mul_f32_e32 v93, v221, v93
	v_mul_f32_e32 v99, v219, v99
	v_mul_f32_e32 v101, v217, v101
	v_mul_f32_e32 v103, v63, v103
	v_mul_f32_e32 v111, v215, v111
	v_mul_f32_e32 v113, v163, v113
	v_mul_f32_e32 v119, v63, v119
	v_mul_f32_e32 v127, v215, v127
	v_mul_f32_e32 v129, v163, v129
	v_mul_f32_e32 v135, v63, v135
	v_mul_f32_e32 v143, v215, v143
	v_mul_f32_e32 v145, v163, v145
	s_waitcnt lgkmcnt(13)
	v_mul_f32_e32 v151, v63, v151
	v_fmac_f32_e32 v59, v214, v78
	v_fmac_f32_e32 v67, v162, v80
	s_waitcnt lgkmcnt(11)
	v_mul_f32_e32 v159, v215, v159
	v_mul_f32_e32 v161, v163, v161
	s_waitcnt lgkmcnt(9)
	v_mul_f32_e32 v175, v63, v175
	v_fmac_f32_e32 v89, v60, v88
	s_waitcnt lgkmcnt(8)
	v_mul_f32_e32 v88, v223, v179
	s_waitcnt lgkmcnt(7)
	v_mul_f32_e32 v179, v215, v183
	v_fmac_f32_e32 v91, v222, v90
	v_mul_f32_e32 v90, v163, v185
	s_waitcnt lgkmcnt(5)
	v_mul_f32_e32 v183, v63, v191
	v_fmac_f32_e32 v95, v214, v94
	v_fmac_f32_e32 v97, v162, v96
	s_waitcnt lgkmcnt(3)
	v_pk_mul_f32 v[74:75], v[214:215], v[198:199]
	v_pk_mul_f32 v[76:77], v[162:163], v[200:201]
	s_waitcnt lgkmcnt(2)
	v_pk_mul_f32 v[78:79], v[218:219], v[202:203]
	v_pk_mul_f32 v[80:81], v[216:217], v[204:205]
	s_waitcnt lgkmcnt(1)
	v_mul_f32_e32 v36, v63, v207
	v_mul_f32_e32 v105, v61, v105
	v_mul_f32_e32 v107, v223, v107
	v_mul_f32_e32 v109, v221, v109
	v_mul_f32_e32 v115, v219, v115
	v_mul_f32_e32 v117, v217, v117
	v_mul_f32_e32 v121, v61, v121
	v_mul_f32_e32 v131, v219, v131
	v_mul_f32_e32 v133, v217, v133
	v_mul_f32_e32 v137, v61, v137
	v_mul_f32_e32 v147, v219, v147
	v_mul_f32_e32 v149, v217, v149
	v_mul_f32_e32 v153, v61, v153
	v_fmac_f32_e32 v224, v218, v82
	v_fmac_f32_e32 v225, v216, v84
	v_mul_f32_e32 v171, v219, v171
	v_mul_f32_e32 v173, v217, v173
	v_fmac_f32_e32 v87, v62, v86
	v_mul_f32_e32 v86, v61, v177
	v_mul_f32_e32 v177, v221, v181
	v_fmac_f32_e32 v93, v220, v92
	v_mul_f32_e32 v92, v219, v187
	v_mul_f32_e32 v181, v217, v189
	v_mul_f32_e32 v94, v61, v193
	s_waitcnt lgkmcnt(0)
	v_mul_f32_e32 v83, v222, v210
	v_fmac_f32_e32 v99, v218, v98
	v_fmac_f32_e32 v101, v216, v100
	v_mul_f32_e32 v82, v61, v209
	v_fmac_f32_e32 v103, v62, v102
	v_fmac_f32_e32 v111, v214, v110
	v_fmac_f32_e32 v113, v162, v112
	v_fmac_f32_e32 v119, v62, v118
	v_fmac_f32_e32 v127, v214, v126
	v_fmac_f32_e32 v129, v162, v128
	v_fmac_f32_e32 v135, v62, v134
	v_fmac_f32_e32 v143, v214, v142
	v_fmac_f32_e32 v145, v162, v144
	v_fmac_f32_e32 v151, v62, v150
	v_fmac_f32_e32 v159, v214, v158
	v_fmac_f32_e32 v161, v162, v160
	v_fmac_f32_e32 v175, v62, v174
	v_fmac_f32_e32 v179, v214, v182
	v_fmac_f32_e32 v90, v162, v184
	v_fmac_f32_e32 v183, v62, v190
	v_pk_mov_b32 v[84:85], v[74:75], v[76:77] op_sel:[1,0]
	v_mov_b32_e32 v75, v77
	v_pk_mov_b32 v[76:77], v[78:79], v[80:81] op_sel:[1,0]
	v_mov_b32_e32 v79, v81
	v_pk_fma_f32 v[62:63], v[62:63], v[206:207], v[36:37] op_sel_hi:[1,1,0]
	v_add_f32_e32 v36, v59, v67
	v_add_f32_e32 v81, v95, v97
	v_mul_f32_e32 v163, v220, v212
	v_mul_f32_e32 v185, v221, v213
	v_fmac_f32_e32 v105, v60, v104
	v_fmac_f32_e32 v107, v222, v106
	v_fmac_f32_e32 v109, v220, v108
	v_fmac_f32_e32 v115, v218, v114
	v_fmac_f32_e32 v117, v216, v116
	v_fmac_f32_e32 v121, v60, v120
	v_fmac_f32_e32 v131, v218, v130
	v_fmac_f32_e32 v133, v216, v132
	v_fmac_f32_e32 v137, v60, v136
	v_fmac_f32_e32 v147, v218, v146
	v_fmac_f32_e32 v149, v216, v148
	v_fmac_f32_e32 v153, v60, v152
	v_fmac_f32_e32 v171, v218, v170
	v_fmac_f32_e32 v173, v216, v172
	v_fmac_f32_e32 v86, v60, v176
	v_fmac_f32_e32 v92, v218, v186
	v_fmac_f32_e32 v181, v216, v188
	v_fmac_f32_e32 v94, v60, v192
	v_pk_fma_f32 v[60:61], v[60:61], v[208:209], v[82:83] op_sel_hi:[1,1,0]
	v_add_f32_e32 v59, v224, v225
	v_add_f32_e32 v80, v91, v93
	v_add_f32_e32 v82, v99, v101
	v_add_f32_e32 v91, v111, v113
	v_add_f32_e32 v98, v127, v129
	v_add_f32_e32 v102, v143, v145
	v_add_f32_e32 v106, v159, v161
	v_add_f32_e32 v90, v179, v90
	v_pk_add_f32 v[74:75], v[84:85], v[74:75]
	v_pk_add_f32 v[76:77], v[76:77], v[78:79]
	v_add_f32_e32 v36, 0, v36
	v_add_f32_e32 v78, 0, v81
	v_mul_f32_e32 v123, v223, v123
	v_mul_f32_e32 v125, v221, v125
	v_mul_f32_e32 v139, v223, v139
	v_mul_f32_e32 v141, v221, v141
	v_mul_f32_e32 v155, v223, v155
	v_mul_f32_e32 v157, v221, v157
	v_mul_f32_e32 v96, v223, v211
	v_mul_f32_e32 v187, v223, v195
	v_mul_f32_e32 v189, v221, v197
	v_add_f32_e32 v67, v87, v89
	v_add_f32_e32 v87, v103, v105
	v_add_f32_e32 v89, v107, v109
	v_add_f32_e32 v93, v115, v117
	v_add_f32_e32 v99, v131, v133
	v_add_f32_e32 v103, v147, v149
	v_add_f32_e32 v107, v171, v173
	v_add_f32_e32 v92, v92, v181
	v_mov_b32_e32 v63, v163
	v_mov_b32_e32 v61, v185
	v_add_f32_e32 v79, 0, v91
	v_add_f32_e32 v81, 0, v98
	v_add_f32_e32 v84, 0, v102
	v_add_f32_e32 v85, 0, v106
	v_add_f32_e32 v90, 0, v90
	v_add_f32_e32 v91, v74, v75
	v_pk_add_f32 v[74:75], v[76:77], v[76:77] op_sel:[0,1] op_sel_hi:[1,0]
	v_add_f32_e32 v36, v36, v59
	v_add_f32_e32 v59, v78, v82
	v_fmac_f32_e32 v123, v222, v122
	v_fmac_f32_e32 v125, v220, v124
	v_fmac_f32_e32 v139, v222, v138
	v_fmac_f32_e32 v141, v220, v140
	v_fmac_f32_e32 v155, v222, v154
	v_fmac_f32_e32 v157, v220, v156
	v_fmac_f32_e32 v88, v222, v178
	v_fmac_f32_e32 v177, v220, v180
	v_fmac_f32_e32 v187, v222, v194
	v_fmac_f32_e32 v189, v220, v196
	v_add_f32_e32 v95, v119, v121
	v_add_f32_e32 v100, v135, v137
	v_add_f32_e32 v104, v151, v153
	v_add_f32_e32 v86, v175, v86
	v_add_f32_e32 v94, v183, v94
	v_pk_add_f32 v[60:61], v[62:63], v[60:61]
	v_add_f32_e32 v62, v79, v93
	v_add_f32_e32 v63, v81, v99
	v_add_f32_e32 v76, v84, v103
	v_add_f32_e32 v77, v85, v107
	v_add_f32_e32 v78, v90, v92
	v_add_f32_e32 v82, 0, v91
	v_mov_b32_e32 v75, v96
	v_add_f32_e32 v36, v36, v67
	v_add_f32_e32 v59, v59, v87
	v_add_f32_e32 v97, v123, v125
	v_add_f32_e32 v101, v139, v141
	v_add_f32_e32 v105, v155, v157
	v_add_f32_e32 v88, v88, v177
	v_add_f32_e32 v108, v187, v189
	v_add_f32_e32 v67, v62, v95
	v_add_f32_e32 v79, v63, v100
	v_add_f32_e32 v76, v76, v104
	v_add_f32_e32 v77, v77, v86
	v_add_f32_e32 v78, v78, v94
	v_pk_add_f32 v[62:63], v[82:83], v[74:75]
	v_add_f32_e32 v36, v36, v80
	v_add_f32_e32 v59, v59, v89
	v_add_f32_e32 v67, v67, v97
	v_add_f32_e32 v74, v79, v101
	v_add_f32_e32 v75, v76, v105
	v_add_f32_e32 v76, v77, v88
	v_add_f32_e32 v77, v78, v108
	v_pk_add_f32 v[60:61], v[62:63], v[60:61]
	s_waitcnt lgkmcnt(0)
; #define LAS __attribute__((address_space(3)))
; __device__ __forceinline__ float wave_sum(float v) {
; #pragma unroll
;     for (int o = 1; o < 64; o <<= 1) v += __shfl_xor(v, o);
;     return v;
; }
; template <int LO, int HI> __global__ void __launch_bounds__(NWAVES * 64, 2) fox_fwd(Args args) {
;     ...
;             for (int q = 0; q < 8; ++q) { float a = 0.f;
; #pragma unroll
;                 for (int j = 0; j < 4; ++j) { const f32x4 w = *(const LAS f32x4*)(wf + q * 1024 + P1COL(j)); a += (v[j][0] * w[0] + v[j][1] * w[1]) + (v[j][2] * w[2] + v[j][3] * w[3]); }
;                 fl[q] = wave_sum(a); }
;             float mine = fl[0];
; #pragma unroll
;             for (int q = 1; q < 8; ++q) mine = (lane == q) ? fl[q] : mine;
;             { const float z = mine + bfv; const float ls = fminf(z, 0.f) - log1pf(__expf(-fabsf(z)));
	v_add_f32_e32 v60, v60, v61
	v_add_f32_dpp v62, v36, v36 quad_perm:[1,0,3,2] row_mask:0xf bank_mask:0xf
	v_add_f32_dpp v63, v59, v59 quad_perm:[1,0,3,2] row_mask:0xf bank_mask:0xf
	v_add_f32_dpp v78, v67, v67 quad_perm:[1,0,3,2] row_mask:0xf bank_mask:0xf
	v_add_f32_dpp v79, v74, v74 quad_perm:[1,0,3,2] row_mask:0xf bank_mask:0xf
	v_add_f32_dpp v80, v75, v75 quad_perm:[1,0,3,2] row_mask:0xf bank_mask:0xf
	v_add_f32_dpp v81, v76, v76 quad_perm:[1,0,3,2] row_mask:0xf bank_mask:0xf
	v_add_f32_dpp v82, v77, v77 quad_perm:[1,0,3,2] row_mask:0xf bank_mask:0xf
	v_add_f32_dpp v61, v60, v60 quad_perm:[1,0,3,2] row_mask:0xf bank_mask:0xf
	v_add_f32_dpp v36, v62, v62 quad_perm:[2,3,0,1] row_mask:0xf bank_mask:0xf
	v_add_f32_dpp v59, v63, v63 quad_perm:[2,3,0,1] row_mask:0xf bank_mask:0xf
	v_add_f32_dpp v67, v78, v78 quad_perm:[2,3,0,1] row_mask:0xf bank_mask:0xf
	v_add_f32_dpp v74, v79, v79 quad_perm:[2,3,0,1] row_mask:0xf bank_mask:0xf
	v_add_f32_dpp v75, v80, v80 quad_perm:[2,3,0,1] row_mask:0xf bank_mask:0xf
	v_add_f32_dpp v76, v81, v81 quad_perm:[2,3,0,1] row_mask:0xf bank_mask:0xf
	v_add_f32_dpp v77, v82, v82 quad_perm:[2,3,0,1] row_mask:0xf bank_mask:0xf
	v_add_f32_dpp v60, v61, v61 quad_perm:[2,3,0,1] row_mask:0xf bank_mask:0xf
	v_add_f32_dpp v62, v36, v36 row_half_mirror row_mask:0xf bank_mask:0xf
	v_add_f32_dpp v63, v59, v59 row_half_mirror row_mask:0xf bank_mask:0xf
	v_add_f32_dpp v78, v67, v67 row_half_mirror row_mask:0xf bank_mask:0xf
	v_add_f32_dpp v79, v74, v74 row_half_mirror row_mask:0xf bank_mask:0xf
	v_add_f32_dpp v80, v75, v75 row_half_mirror row_mask:0xf bank_mask:0xf
	v_add_f32_dpp v81, v76, v76 row_half_mirror row_mask:0xf bank_mask:0xf
	v_add_f32_dpp v82, v77, v77 row_half_mirror row_mask:0xf bank_mask:0xf
	v_add_f32_dpp v61, v60, v60 row_half_mirror row_mask:0xf bank_mask:0xf
	v_add_f32_dpp v36, v62, v62 row_mirror row_mask:0xf bank_mask:0xf
	v_add_f32_dpp v59, v63, v63 row_mirror row_mask:0xf bank_mask:0xf
	v_add_f32_dpp v67, v78, v78 row_mirror row_mask:0xf bank_mask:0xf
	v_add_f32_dpp v74, v79, v79 row_mirror row_mask:0xf bank_mask:0xf
	v_add_f32_dpp v75, v80, v80 row_mirror row_mask:0xf bank_mask:0xf
	v_add_f32_dpp v76, v81, v81 row_mirror row_mask:0xf bank_mask:0xf
	v_add_f32_dpp v77, v82, v82 row_mirror row_mask:0xf bank_mask:0xf
	v_add_f32_dpp v60, v61, v61 row_mirror row_mask:0xf bank_mask:0xf
	v_mov_b32_e32 v62, v36
	v_mov_b32_e32 v63, v59
	v_mov_b32_e32 v78, v67
	v_mov_b32_e32 v79, v74
	v_mov_b32_e32 v80, v75
	v_mov_b32_e32 v81, v76
	v_mov_b32_e32 v82, v77
	v_mov_b32_e32 v61, v60
	v_permlane16_swap_b32_e32 v62, v36
	v_permlane16_swap_b32_e32 v63, v59
	v_permlane16_swap_b32_e32 v78, v67
	v_permlane16_swap_b32_e32 v79, v74
	v_permlane16_swap_b32_e32 v80, v75
	v_permlane16_swap_b32_e32 v81, v76
	v_permlane16_swap_b32_e32 v82, v77
	v_permlane16_swap_b32_e32 v61, v60
	v_add_f32_e32 v62, v62, v36
	v_add_f32_e32 v63, v63, v59
	v_add_f32_e32 v78, v78, v67
	v_add_f32_e32 v79, v79, v74
	v_add_f32_e32 v80, v80, v75
	v_add_f32_e32 v81, v81, v76
	v_add_f32_e32 v82, v82, v77
	v_add_f32_e32 v61, v61, v60
	v_mov_b32_e32 v36, v62
	v_mov_b32_e32 v59, v63
	v_mov_b32_e32 v67, v78
	v_mov_b32_e32 v74, v79
	v_mov_b32_e32 v75, v80
	v_mov_b32_e32 v76, v81
	v_mov_b32_e32 v77, v82
	v_mov_b32_e32 v60, v61
	v_permlane32_swap_b32_e32 v36, v62
	v_permlane32_swap_b32_e32 v59, v63
	v_permlane32_swap_b32_e32 v67, v78
	v_permlane32_swap_b32_e32 v74, v79
	v_permlane32_swap_b32_e32 v75, v80
	v_permlane32_swap_b32_e32 v76, v81
	v_permlane32_swap_b32_e32 v77, v82
	v_permlane32_swap_b32_e32 v60, v61
	v_add_f32_e32 v36, v36, v62
	v_add_f32_e32 v59, v59, v63
	v_add_f32_e32 v62, v67, v78
	v_add_f32_e32 v63, v74, v79
	v_add_f32_e32 v67, v75, v80
	v_add_f32_e32 v74, v76, v81
	v_add_f32_e32 v75, v77, v82
	v_add_f32_e32 v60, v60, v61
	v_cndmask_b32_e64 v36, v36, v59, s[4:5]
	v_cndmask_b32_e64 v36, v36, v62, s[6:7]
	v_cndmask_b32_e64 v36, v36, v63, s[8:9]
	v_cndmask_b32_e64 v36, v36, v67, s[10:11]
	v_cndmask_b32_e64 v36, v36, v74, s[12:13]
	v_cndmask_b32_e64 v36, v36, v75, s[14:15]
	v_cndmask_b32_e64 v36, v36, v60, s[16:17]
	v_add_f32_e32 v36, v71, v36
	v_min_f32_e32 v67, 0, v36
	v_mul_f32_e64 v36, |v36|, s29
	v_exp_f32_e32 v36, v36
	v_lshl_add_u64 v[56:57], v[56:57], 0, s[40:41]
	v_add_f32_e32 v59, 1.0, v36
	v_add_f32_e32 v62, -1.0, v59
	v_frexp_mant_f32_e32 v63, v59
	v_cvt_f64_f32_e32 v[60:61], v59
	v_sub_f32_e32 v74, v62, v59
	v_frexp_exp_i32_f64_e32 v60, v[60:61]
	v_cmp_gt_f32_e32 vcc, s37, v63
	v_sub_f32_e32 v62, v36, v62
	v_add_f32_e32 v61, 1.0, v74
	v_subbrev_co_u32_e32 v60, vcc, 0, v60, vcc
	v_add_f32_e32 v61, v62, v61
	v_sub_u32_e32 v62, 0, v60
	v_ldexp_f32 v59, v59, v62
	v_ldexp_f32 v61, v61, v62
	v_add_f32_e32 v62, -1.0, v59
	v_add_f32_e32 v74, 1.0, v59
	v_add_f32_e32 v63, 1.0, v62
	v_add_f32_e32 v75, -1.0, v74
	v_sub_f32_e32 v63, v59, v63
	v_sub_f32_e32 v59, v59, v75
	v_add_f32_e32 v59, v61, v59
	v_add_f32_e32 v75, v61, v63
	v_add_f32_e32 v61, v74, v59
	v_rcp_f32_e32 v78, v61
	v_add_f32_e32 v63, v62, v75
	v_sub_f32_e32 v74, v61, v74
	v_sub_f32_e32 v59, v59, v74
	v_mul_f32_e32 v80, v63, v78
	v_mul_f32_e32 v74, v61, v80
	v_fma_f32 v76, v80, v61, -v74
	v_sub_f32_e32 v62, v63, v62
	v_fmac_f32_e32 v76, v80, v59
	v_sub_f32_e32 v79, v75, v62
	v_add_f32_e32 v62, v74, v76
; template <int LO, int HI> __global__ void __launch_bounds__(NWAVES * 64, 2) fox_fwd(Args args) {
;     ...
;             { const float z = mine + bfv; const float ls = fminf(z, 0.f) - log1pf(__expf(-fabsf(z)));
; #pragma unroll
;               for (int k = 0; k < 4; ++k)
; #pragma unroll
;                   for (int e = 0; e < 4; ++e) lsq[k][e] = (r == 4 * k + e) ? ls : lsq[k][e]; }
;         }
;         if (lane < 8) { f32x4* dst = (f32x4*)(LF + (size_t)(b * 8 + lane) * T + (m0 - b * T));
; #pragma unroll
;             for (int k = 0; k < 4; ++k) dst[k] = lsq[k]; }
	v_sub_f32_e32 v75, v63, v62
	v_mov_b32_e32 v77, v62
	v_pk_add_f32 v[62:63], v[62:63], v[74:75] neg_lo:[0,1] neg_hi:[0,1]
	v_cvt_f32_i32_e32 v60, v60
	v_pk_add_f32 v[62:63], v[62:63], v[76:77] neg_lo:[0,1] neg_hi:[0,1]
	v_cmp_neq_f32_e32 vcc, s46, v36
	v_add_f32_e32 v63, v79, v63
	v_add_f32_e32 v62, v62, v63
	v_add_f32_e32 v63, v75, v62
	v_mul_f32_e32 v77, v78, v63
	v_mul_f32_e32 v74, v61, v77
	v_fma_f32 v76, v77, v61, -v74
	v_sub_f32_e32 v75, v75, v63
	v_fmac_f32_e32 v76, v77, v59
	v_add_f32_e32 v79, v62, v75
	v_add_f32_e32 v81, v80, v77
	v_add_f32_e32 v62, v74, v76
	v_sub_f32_e32 v61, v81, v80
	v_sub_f32_e32 v75, v63, v62
	v_sub_f32_e32 v59, v77, v61
	v_mov_b32_e32 v77, v62
	v_pk_add_f32 v[62:63], v[62:63], v[74:75] neg_lo:[0,1] neg_hi:[0,1]
	s_nop 0
	v_pk_add_f32 v[62:63], v[62:63], v[76:77] neg_lo:[0,1] neg_hi:[0,1]
	s_nop 0
	v_add_f32_e32 v61, v79, v63
	v_add_f32_e32 v61, v62, v61
	v_add_f32_e32 v61, v75, v61
	v_mul_f32_e32 v61, v78, v61
	v_add_f32_e32 v59, v59, v61
	v_add_f32_e32 v61, v81, v59
	v_mul_f32_e32 v62, v61, v61
	v_sub_f32_e32 v74, v61, v81
	v_fmamk_f32 v75, v62, 0x3e9b6dac, v20
	v_ldexp_f32 v63, v61, 1
	v_sub_f32_e32 v74, v59, v74
	v_mul_f32_e32 v61, v61, v62
	v_fmaak_f32 v59, v62, v75, 0x3f2aaada
	v_ldexp_f32 v77, v74, 1
	v_pk_mul_f32 v[74:75], v[60:61], v[58:59]
	s_nop 0
	v_fma_f32 v62, v60, s36, -v74
	v_fmac_f32_e32 v62, 0xb102e308, v60
	v_pk_add_f32 v[60:61], v[74:75], v[62:63]
	v_mov_b32_e32 v76, v74
	v_sub_f32_e32 v59, v61, v63
	v_sub_f32_e32 v59, v75, v59
	v_add_f32_e32 v77, v77, v59
	v_pk_add_f32 v[78:79], v[60:61], v[74:75] neg_lo:[0,1] neg_hi:[0,1]
	v_pk_add_f32 v[74:75], v[60:61], v[76:77]
	v_mov_b32_e32 v63, v60
	v_mov_b32_e32 v79, v75
	v_pk_add_f32 v[82:83], v[62:63], v[78:79] neg_lo:[0,1] neg_hi:[0,1]
	v_pk_add_f32 v[62:63], v[62:63], v[78:79]
	v_mov_b32_e32 v81, v60
	v_pk_add_f32 v[78:79], v[62:63], v[60:61] op_sel:[1,0] op_sel_hi:[0,1] neg_lo:[0,1] neg_hi:[0,1]
	v_mov_b32_e32 v80, v77
	v_mov_b32_e32 v76, v75
	v_mov_b32_e32 v77, v63
	v_pk_mov_b32 v[60:61], v[60:61], v[78:79] op_sel:[1,0]
	v_pk_add_f32 v[74:75], v[74:75], v[78:79] op_sel_hi:[1,0] neg_lo:[0,1] neg_hi:[0,1]
	v_pk_add_f32 v[60:61], v[76:77], v[60:61] neg_lo:[0,1] neg_hi:[0,1]
	v_mov_b32_e32 v74, v82
	v_pk_add_f32 v[60:61], v[80:81], v[60:61] neg_lo:[0,1] neg_hi:[0,1]
	v_mov_b32_e32 v83, v63
	v_pk_add_f32 v[74:75], v[74:75], v[60:61]
	s_nop 0
	v_pk_add_f32 v[76:77], v[74:75], v[74:75] op_sel:[0,1] op_sel_hi:[1,0]
	s_nop 0
	v_pk_add_f32 v[62:63], v[62:63], v[76:77] op_sel:[1,0] op_sel_hi:[0,1]
	v_mov_b32_e32 v75, v62
	v_mov_b32_e32 v61, v76
	v_pk_add_f32 v[76:77], v[74:75], v[82:83] neg_lo:[0,1] neg_hi:[0,1]
	s_nop 0
	v_sub_f32_e32 v59, v74, v76
	v_pk_add_f32 v[60:61], v[60:61], v[76:77] neg_lo:[0,1] neg_hi:[0,1]
	v_sub_f32_e32 v59, v82, v59
	v_add_f32_e32 v59, v60, v59
	v_add_f32_e32 v59, v59, v61
	v_add_f32_e32 v59, v62, v59
	v_cndmask_b32_e32 v59, v64, v59, vcc
	v_cmp_ngt_f32_e32 vcc, -1.0, v36
	s_nop 1
	v_cndmask_b32_e32 v59, v65, v59, vcc
	v_cmp_neq_f32_e32 vcc, -1.0, v36
	s_nop 1
	v_cndmask_b32_e32 v59, v66, v59, vcc
	v_cmp_lt_f32_e64 vcc, |v36|, s47
	s_nop 1
	v_cndmask_b32_e32 v36, v59, v36, vcc
	v_sub_f32_e32 v36, v67, v36
	s_cselect_b64 vcc, -1, 0
	s_cmpk_eq_i32 s30, 0x1000
	v_cndmask_b32_e32 v37, v37, v36, vcc
	s_cselect_b64 vcc, -1, 0
	s_cmpk_eq_i32 s30, 0x2000
	v_cndmask_b32_e32 v21, v21, v36, vcc
	s_cselect_b64 vcc, -1, 0
	s_cmpk_eq_i32 s30, 0x3000
	v_cndmask_b32_e32 v30, v30, v36, vcc
	s_cselect_b64 vcc, -1, 0
	s_cmpk_eq_i32 s30, 0x4000
	v_cndmask_b32_e32 v31, v31, v36, vcc
	s_cselect_b64 vcc, -1, 0
	s_cmpk_eq_i32 s30, 0x5000
	v_cndmask_b32_e32 v32, v32, v36, vcc
	s_cselect_b64 vcc, -1, 0
	s_cmpk_eq_i32 s30, 0x6000
	v_cndmask_b32_e32 v33, v33, v36, vcc
	s_cselect_b64 vcc, -1, 0
	s_cmpk_eq_i32 s30, 0x7000
	v_cndmask_b32_e32 v26, v26, v36, vcc
	s_cselect_b64 vcc, -1, 0
	s_cmpk_eq_u32 s30, 0x8000
	v_cndmask_b32_e32 v27, v27, v36, vcc
	s_cselect_b64 vcc, -1, 0
	s_cmpk_eq_u32 s30, 0x9000
	v_cndmask_b32_e32 v28, v28, v36, vcc
	s_cselect_b64 vcc, -1, 0
	s_cmpk_eq_u32 s30, 0xa000
	v_cndmask_b32_e32 v29, v29, v36, vcc
	s_cselect_b64 vcc, -1, 0
	s_cmpk_eq_u32 s30, 0xb000
	v_cndmask_b32_e32 v22, v22, v36, vcc
	s_cselect_b64 vcc, -1, 0
	s_cmpk_eq_u32 s30, 0xc000
	v_cndmask_b32_e32 v23, v23, v36, vcc
	s_cselect_b64 vcc, -1, 0
	s_cmpk_eq_u32 s30, 0xd000
	v_cndmask_b32_e32 v24, v24, v36, vcc
	s_cselect_b64 vcc, -1, 0
	s_add_u32 s30, s30, 0x1000
	s_addc_u32 s31, s31, 0
	s_cmpk_eq_u32 s30, 0xe000
	v_cndmask_b32_e32 v25, v25, v36, vcc
	s_cbranch_scc0 .LBB0_131
	v_cmp_gt_u32_e32 vcc, 8, v1
	s_and_saveexec_b64 s[4:5], vcc
	s_cbranch_execz .LBB0_134
	v_lshl_or_b32 v2, s44, 3, v1
	v_ashrrev_i32_e32 v3, 31, v2
	s_lshl_b32 s6, s44, 12
	v_lshlrev_b64 v[2:3], 14, v[2:3]
	s_sub_i32 s6, s28, s6
	v_lshl_add_u64 v[2:3], s[26:27], 0, v[2:3]
	s_ashr_i32 s7, s6, 31
	v_lshl_add_u64 v[2:3], s[6:7], 2, v[2:3]
	s_mov_b64 s[6:7], 0x100000
	v_lshl_add_u64 v[4:5], v[2:3], 0, s[6:7]
	v_add_co_u32_e32 v2, vcc, 0x100000, v2
	v_mov_b32_e32 v20, v37
	s_nop 0
	v_addc_co_u32_e32 v3, vcc, 0, v3, vcc
	global_store_dwordx4 v[2:3], v[18:21], off
	global_store_dwordx4 v[4:5], v[30:33], off offset:16
	global_store_dwordx4 v[4:5], v[26:29], off offset:32
	global_store_dwordx4 v[4:5], v[22:25], off offset:48
